# fox staging waves: scalar base + 32-bit lane offset instead of the per-tile 64-bit VALU address chain
# baseline (speedup 1.0000x reference)
; DI void fox_unit(const Params& p, int hf, int bl, int fh, int qb, unsigned char* shm, int tid, bool dry = false) {
;     ...
;     if (kt + 1 < nkt) {
;       const size_t r = (size_t)((kt + 1) * 64 + skey) * NP;
;       kreg = *(const uint4*)(projb + r + C_FK + fh * 64 + sdg * 8); vreg = *(const uint4*)(projb + r + C_FV + fh * 64 + sdg * 8);
;       if (tid < 64) freg = (Fref - F[(kt + 1) * 64 + tid]) * LOG2E;
;     }
.LBB0_486:
	s_cmp_lg_u32 s99, 0
	s_cbranch_scc1 .Lfox1_noload
	s_mul_i32 s100, s18, 0x3400
	s_add_u32 s100, s100, s6
	s_addc_u32 s101, s7, 0
	s_add_u32 s100, s100, s2
	s_addc_u32 s101, s101, s3
	s_add_u32 s100, s100, 0x1c00
	s_addc_u32 s101, s101, 0
	s_add_u32 s4, s100, 0x68000
	s_addc_u32 s5, s101, 0
	v_mov_b32_e32 v24, 0x3400
	v_mad_u32_u24 v24, v217, v24, v160
	global_load_dwordx4 v[16:19], v24, s[100:101]
	global_load_dwordx4 v[20:23], v24, s[100:101] offset:1024
	global_load_dwordx4 v[196:199], v24, s[4:5]
	global_load_dwordx2 v[170:171], v24, s[4:5] offset:1024
	global_load_dword v162, v24, s[4:5] offset:1032
	global_load_dword v168, v24, s[4:5] offset:1036
	s_and_saveexec_b64 s[4:5], s[0:1]
	s_cbranch_execz .LBB0_488
	v_add_u32_e32 v24, s18, v216
	v_ashrrev_i32_e32 v25, 31, v24
	v_lshl_add_u64 v[24:25], v[24:25], 2, s[8:9]
	global_load_dword v208, v[24:25], off

; DI void fox_unit(const Params& p, int hf, int bl, int fh, int qb, unsigned char* shm, int tid, bool dry = false) {
;     ...
;     if (kt + 1 < nkt) {
;       const size_t r = (size_t)((kt + 1) * 64 + skey) * NP;
;       kreg = *(const uint4*)(projb + r + C_FK + fh * 64 + sdg * 8); vreg = *(const uint4*)(projb + r + C_FV + fh * 64 + sdg * 8);
;       if (tid < 64) freg = (Fref - F[(kt + 1) * 64 + tid]) * LOG2E;
;     }
.LBB0_606:
	s_cmp_lg_u32 s99, 0
	s_cbranch_scc1 .Lfox2_noload
	s_mul_i32 s100, s17, 0x3400
	s_add_u32 s100, s100, s6
	s_addc_u32 s101, s7, 0
	s_add_u32 s100, s100, s2
	s_addc_u32 s101, s101, s3
	s_add_u32 s100, s100, 0x1c00
	s_addc_u32 s101, s101, 0
	s_add_u32 s4, s100, 0x68000
	s_addc_u32 s5, s101, 0
	v_mov_b32_e32 v24, 0x3400
	v_mad_u32_u24 v24, v217, v24, v160
	global_load_dwordx4 v[16:19], v24, s[100:101]
	global_load_dwordx4 v[20:23], v24, s[100:101] offset:1024
	global_load_dwordx4 v[196:199], v24, s[4:5]
	global_load_dwordx2 v[170:171], v24, s[4:5] offset:1024
	global_load_dword v162, v24, s[4:5] offset:1032
	global_load_dword v168, v24, s[4:5] offset:1036
	s_and_saveexec_b64 s[4:5], s[0:1]
	s_cbranch_execz .LBB0_608
	v_add_u32_e32 v24, s17, v216
	v_ashrrev_i32_e32 v25, 31, v24
	v_lshl_add_u64 v[24:25], v[24:25], 2, s[8:9]
	global_load_dword v208, v[24:25], off
